# dilated attention: the four O read-back LDS reads of the first write-out block issued together (were read-wait-store chained)
# baseline (speedup 1.0000x reference)
.LBB0_128:
	v_mov_b32_e32 v100, v213
	v_cvt_pk_bf16_f32 v48, v2, v3
	v_cvt_pk_bf16_f32 v134, v54, v55
	v_bfe_u32 v0, v100, 2, 2
	v_lshrrev_b32_e32 v1, 3, v100
	v_bfe_u32 v2, v100, 1, 1
	v_and_or_b32 v54, v1, 2, v2
	v_lshlrev_b32_e32 v55, 2, v0
	v_lshlrev_b32_e32 v1, 3, v100
	v_or_b32_e32 v151, 16, v180
	v_cvt_pk_bf16_f32 v149, v52, v53
	v_and_b32_e32 v152, 8, v1
	v_or_b32_e32 v52, v55, v226
	v_or_b32_e32 v1, v0, v151
	v_lshlrev_b32_e32 v153, 8, v1
	v_bitop3_b32 v1, v55, v54, v226 bitop3:0x36
	v_or_b32_e32 v0, v0, v180
	v_bitop3_b32 v2, v52, v54, 2 bitop3:0x36
	v_cvt_pk_bf16_f32 v131, v16, v17
	v_cvt_pk_bf16_f32 v132, v18, v19
	v_lshlrev_b32_e32 v53, 8, v0
	v_lshl_add_u32 v16, v1, 4, s80
	v_lshl_add_u32 v18, v2, 4, s80
	v_cvt_pk_bf16_f32 v133, v20, v21
	v_add3_u32 v20, v16, v53, v152
	v_add3_u32 v21, v18, v53, v152
	v_cvt_pk_bf16_f32 v49, v4, v5
	v_cvt_pk_bf16_f32 v50, v6, v7
	v_cvt_pk_bf16_f32 v51, v8, v9
	ds_read_b64_tr_b16 v[0:1], v20
	ds_read_b64_tr_b16 v[2:3], v21 offset:2048
	v_or_b32_e32 v154, 0x800, v153
	v_cvt_pk_bf16_f32 v72, v22, v23
	v_add3_u32 v22, v16, v153, v152
	v_add3_u32 v23, v18, v154, v152
	v_cvt_pk_bf16_f32 v142, v10, v11
	v_cvt_pk_bf16_f32 v143, v12, v13
	v_cvt_pk_bf16_f32 v144, v14, v15
	ds_read_b64_tr_b16 v[16:17], v22
	ds_read_b64_tr_b16 v[18:19], v23
	s_waitcnt lgkmcnt(2)
	v_mfma_f32_32x32x16_bf16 v[0:15], v[48:51], v[0:3], 0
	v_cvt_pk_bf16_f32 v145, v30, v31
	v_cvt_pk_bf16_f32 v146, v64, v65
	v_cvt_pk_bf16_f32 v147, v66, v67
	v_cvt_pk_bf16_f32 v148, v68, v69
	v_cvt_pk_bf16_f32 v135, v56, v57
	v_cvt_pk_bf16_f32 v136, v58, v59
	v_cvt_pk_bf16_f32 v137, v62, v63
	ds_read_b64_tr_b16 v[244:245], v20 offset:8192
	ds_read_b64_tr_b16 v[246:247], v21 offset:10240
	s_waitcnt lgkmcnt(2)
	v_mfma_f32_32x32x16_bf16 v[0:15], v[142:145], v[16:19], v[0:15]
	v_cvt_pk_bf16_f32 v138, v32, v33
	v_cvt_pk_bf16_f32 v139, v34, v35
	v_cvt_pk_bf16_f32 v140, v36, v37
	v_cvt_pk_bf16_f32 v141, v38, v39
	v_cvt_pk_bf16_f32 v76, v40, v41
	v_cvt_pk_bf16_f32 v77, v42, v43
	ds_read_b64_tr_b16 v[16:17], v22 offset:8192
	ds_read_b64_tr_b16 v[18:19], v23 offset:8192
	s_waitcnt lgkmcnt(2)
	v_mfma_f32_32x32x16_bf16 v[0:15], v[146:149], v[244:247], v[0:15]
	v_cvt_pk_bf16_f32 v78, v44, v45
	v_cvt_pk_bf16_f32 v79, v46, v47
	v_cvt_pk_bf16_f32 v130, v60, v61
	v_cvt_pk_bf16_f32 v73, v24, v25
	v_cvt_pk_bf16_f32 v74, v26, v27
	v_cvt_pk_bf16_f32 v75, v28, v29
	ds_read_b64_tr_b16 v[244:245], v20 offset:16384
	ds_read_b64_tr_b16 v[246:247], v21 offset:18432
	s_waitcnt lgkmcnt(2)
	v_mfma_f32_32x32x16_bf16 v[0:15], v[134:137], v[16:19], v[0:15]
	v_cvt_pk_bf16_f32 v68, v70, v178
	v_cvt_pk_bf16_f32 v69, v71, v179
	v_cvt_pk_bf16_f32 v70, v182, v183
	v_cvt_pk_bf16_f32 v71, v184, v185
	v_cvt_pk_bf16_f32 v64, v186, v187
	v_cvt_pk_bf16_f32 v65, v188, v189
	ds_read_b64_tr_b16 v[16:17], v22 offset:16384
	ds_read_b64_tr_b16 v[18:19], v23 offset:16384
	s_waitcnt lgkmcnt(2)
	v_mfma_f32_32x32x16_bf16 v[0:15], v[138:141], v[244:247], v[0:15]
	v_cvt_pk_bf16_f32 v66, v190, v191
	v_cvt_pk_bf16_f32 v67, v192, v193
	s_cmp_lt_i32 s89, 0
	s_cselect_b64 s[28:29], -1, 0
	s_cmp_gt_i32 s89, -1
	s_cselect_b64 s[30:31], -1, 0
	ds_read_b64_tr_b16 v[244:245], v20 offset:24576
	ds_read_b64_tr_b16 v[246:247], v21 offset:26624
	s_waitcnt lgkmcnt(2)
	v_mfma_f32_32x32x16_bf16 v[0:15], v[76:79], v[16:19], v[0:15]
	s_and_b64 vcc, exec, s[28:29]
	ds_read_b64_tr_b16 v[16:17], v22 offset:24576
	ds_read_b64_tr_b16 v[18:19], v23 offset:24576
	s_waitcnt lgkmcnt(2)
	v_mfma_f32_32x32x16_bf16 v[0:15], v[130:133], v[244:247], v[0:15]
	ds_read_b64_tr_b16 v[244:245], v20 offset:32768
	ds_read_b64_tr_b16 v[246:247], v21 offset:34816
	s_waitcnt lgkmcnt(2)
	v_mfma_f32_32x32x16_bf16 v[0:15], v[72:75], v[16:19], v[0:15]
	ds_read_b64_tr_b16 v[16:17], v22 offset:32768
	ds_read_b64_tr_b16 v[18:19], v23 offset:32768
	s_waitcnt lgkmcnt(2)
	v_mfma_f32_32x32x16_bf16 v[0:15], v[68:71], v[244:247], v[0:15]
	s_waitcnt lgkmcnt(0)
	v_mfma_f32_32x32x16_bf16 v[0:15], v[64:67], v[16:19], v[0:15]
	v_or_b32_e32 v18, 4, v54
	v_bitop3_b32 v16, v55, v18, v226 bitop3:0x36
	v_bitop3_b32 v18, v52, v18, 2 bitop3:0x36
	v_lshl_add_u32 v32, v16, 4, s80
	v_lshl_add_u32 v34, v18, 4, s80
	v_add3_u32 v36, v32, v53, v152
	v_add3_u32 v37, v34, v53, v152
	ds_read_b64_tr_b16 v[16:17], v36
	ds_read_b64_tr_b16 v[18:19], v37 offset:2048
	v_add3_u32 v38, v32, v153, v152
	v_add3_u32 v39, v34, v154, v152
	ds_read_b64_tr_b16 v[32:33], v38
	ds_read_b64_tr_b16 v[34:35], v39
	s_waitcnt lgkmcnt(2)
	v_mfma_f32_32x32x16_bf16 v[16:31], v[48:51], v[16:19], 0
	ds_read_b64_tr_b16 v[244:245], v36 offset:8192
	ds_read_b64_tr_b16 v[246:247], v37 offset:10240
	s_waitcnt lgkmcnt(2)
	v_mfma_f32_32x32x16_bf16 v[16:31], v[142:145], v[32:35], v[16:31]
	ds_read_b64_tr_b16 v[32:33], v38 offset:8192
	ds_read_b64_tr_b16 v[34:35], v39 offset:8192
	s_waitcnt lgkmcnt(2)
	v_mfma_f32_32x32x16_bf16 v[16:31], v[146:149], v[244:247], v[16:31]
	ds_read_b64_tr_b16 v[244:245], v36 offset:16384
	ds_read_b64_tr_b16 v[246:247], v37 offset:18432
	s_waitcnt lgkmcnt(2)
	v_mfma_f32_32x32x16_bf16 v[16:31], v[134:137], v[32:35], v[16:31]
	ds_read_b64_tr_b16 v[32:33], v38 offset:16384
	ds_read_b64_tr_b16 v[34:35], v39 offset:16384
	s_waitcnt lgkmcnt(2)
	v_mfma_f32_32x32x16_bf16 v[16:31], v[138:141], v[244:247], v[16:31]
	ds_read_b64_tr_b16 v[244:245], v36 offset:24576
	ds_read_b64_tr_b16 v[246:247], v37 offset:26624
	s_waitcnt lgkmcnt(2)
	v_mfma_f32_32x32x16_bf16 v[16:31], v[76:79], v[32:35], v[16:31]
	ds_read_b64_tr_b16 v[32:33], v38 offset:24576
	ds_read_b64_tr_b16 v[34:35], v39 offset:24576
	s_waitcnt lgkmcnt(2)
	v_mfma_f32_32x32x16_bf16 v[16:31], v[130:133], v[244:247], v[16:31]
	ds_read_b64_tr_b16 v[244:245], v36 offset:32768
	ds_read_b64_tr_b16 v[246:247], v37 offset:34816
	s_waitcnt lgkmcnt(2)
	v_mfma_f32_32x32x16_bf16 v[16:31], v[72:75], v[32:35], v[16:31]
	ds_read_b64_tr_b16 v[32:33], v38 offset:32768
	ds_read_b64_tr_b16 v[34:35], v39 offset:32768
	s_waitcnt lgkmcnt(2)
	v_mfma_f32_32x32x16_bf16 v[16:31], v[68:71], v[244:247], v[16:31]
	s_waitcnt lgkmcnt(0)
	v_mfma_f32_32x32x16_bf16 v[16:31], v[64:67], v[32:35], v[16:31]
	v_or_b32_e32 v34, 8, v54
	v_bitop3_b32 v32, v55, v34, v226 bitop3:0x36
	v_bitop3_b32 v34, v52, v34, 2 bitop3:0x36
	v_lshl_add_u32 v56, v32, 4, s80
	v_lshl_add_u32 v58, v34, 4, s80
	v_add3_u32 v60, v56, v53, v152
	v_add3_u32 v61, v58, v53, v152
	ds_read_b64_tr_b16 v[32:33], v60
	ds_read_b64_tr_b16 v[34:35], v61 offset:2048
	v_add3_u32 v62, v56, v153, v152
	v_add3_u32 v63, v58, v154, v152
	ds_read_b64_tr_b16 v[56:57], v62
	ds_read_b64_tr_b16 v[58:59], v63
	s_waitcnt lgkmcnt(2)
	v_mfma_f32_32x32x16_bf16 v[32:47], v[48:51], v[32:35], 0
	ds_read_b64_tr_b16 v[244:245], v60 offset:8192
	ds_read_b64_tr_b16 v[246:247], v61 offset:10240
	s_waitcnt lgkmcnt(2)
	v_mfma_f32_32x32x16_bf16 v[32:47], v[142:145], v[56:59], v[32:47]
	ds_read_b64_tr_b16 v[56:57], v62 offset:8192
	ds_read_b64_tr_b16 v[58:59], v63 offset:8192
	s_waitcnt lgkmcnt(2)
	v_mfma_f32_32x32x16_bf16 v[32:47], v[146:149], v[244:247], v[32:47]
	ds_read_b64_tr_b16 v[244:245], v60 offset:16384
	ds_read_b64_tr_b16 v[246:247], v61 offset:18432
	s_waitcnt lgkmcnt(2)
	v_mfma_f32_32x32x16_bf16 v[32:47], v[134:137], v[56:59], v[32:47]
	ds_read_b64_tr_b16 v[56:57], v62 offset:16384
	ds_read_b64_tr_b16 v[58:59], v63 offset:16384
	s_waitcnt lgkmcnt(2)
	v_mfma_f32_32x32x16_bf16 v[32:47], v[138:141], v[244:247], v[32:47]
	ds_read_b64_tr_b16 v[244:245], v60 offset:24576
	ds_read_b64_tr_b16 v[246:247], v61 offset:26624
	s_waitcnt lgkmcnt(2)
	v_mfma_f32_32x32x16_bf16 v[32:47], v[76:79], v[56:59], v[32:47]
	ds_read_b64_tr_b16 v[56:57], v62 offset:24576
	ds_read_b64_tr_b16 v[58:59], v63 offset:24576
	s_waitcnt lgkmcnt(2)
	v_mfma_f32_32x32x16_bf16 v[32:47], v[130:133], v[244:247], v[32:47]
	ds_read_b64_tr_b16 v[244:245], v60 offset:32768
	ds_read_b64_tr_b16 v[246:247], v61 offset:34816
	s_waitcnt lgkmcnt(2)
	v_mfma_f32_32x32x16_bf16 v[32:47], v[72:75], v[56:59], v[32:47]
	ds_read_b64_tr_b16 v[56:57], v62 offset:32768
	ds_read_b64_tr_b16 v[58:59], v63 offset:32768
	s_waitcnt lgkmcnt(2)
	v_mfma_f32_32x32x16_bf16 v[32:47], v[68:71], v[244:247], v[32:47]
	s_waitcnt lgkmcnt(0)
	v_mfma_f32_32x32x16_bf16 v[32:47], v[64:67], v[56:59], v[32:47]
	v_or_b32_e32 v56, 12, v54
	v_bitop3_b32 v54, v55, v56, v226 bitop3:0x36
	v_bitop3_b32 v52, v52, v56, 2 bitop3:0x36
	v_lshl_add_u32 v155, v54, 4, s80
	v_lshl_add_u32 v158, v52, 4, s80
	v_add3_u32 v160, v155, v53, v152
	v_add3_u32 v161, v158, v53, v152
	ds_read_b64_tr_b16 v[54:55], v160
	ds_read_b64_tr_b16 v[56:57], v161 offset:2048
	v_add3_u32 v153, v155, v153, v152
	ds_read_b64_tr_b16 v[156:157], v153
	s_waitcnt lgkmcnt(1)
	v_mfma_f32_32x32x16_bf16 v[48:63], v[48:51], v[54:57], 0
	v_add3_u32 v152, v158, v154, v152
	ds_read_b64_tr_b16 v[158:159], v152
	ds_read_b64_tr_b16 v[244:245], v160 offset:8192
	ds_read_b64_tr_b16 v[246:247], v161 offset:10240
	s_waitcnt lgkmcnt(2)
	v_mfma_f32_32x32x16_bf16 v[48:63], v[142:145], v[156:159], v[48:63]
	ds_read_b64_tr_b16 v[156:157], v153 offset:8192
	ds_read_b64_tr_b16 v[158:159], v152 offset:8192
	s_waitcnt lgkmcnt(2)
	v_mfma_f32_32x32x16_bf16 v[48:63], v[146:149], v[244:247], v[48:63]
	ds_read_b64_tr_b16 v[244:245], v160 offset:16384
	ds_read_b64_tr_b16 v[246:247], v161 offset:18432
	s_waitcnt lgkmcnt(2)
	v_mfma_f32_32x32x16_bf16 v[48:63], v[134:137], v[156:159], v[48:63]
	ds_read_b64_tr_b16 v[156:157], v153 offset:16384
	ds_read_b64_tr_b16 v[158:159], v152 offset:16384
	s_waitcnt lgkmcnt(2)
	v_mfma_f32_32x32x16_bf16 v[48:63], v[138:141], v[244:247], v[48:63]
	ds_read_b64_tr_b16 v[244:245], v160 offset:24576
	ds_read_b64_tr_b16 v[246:247], v161 offset:26624
	s_waitcnt lgkmcnt(2)
	v_mfma_f32_32x32x16_bf16 v[48:63], v[76:79], v[156:159], v[48:63]
	ds_read_b64_tr_b16 v[156:157], v153 offset:24576
	ds_read_b64_tr_b16 v[158:159], v152 offset:24576
	s_waitcnt lgkmcnt(2)
	v_mfma_f32_32x32x16_bf16 v[48:63], v[130:133], v[244:247], v[48:63]
	v_ashrrev_i32_e32 v133, 3, v100
	v_lshlrev_b32_e32 v100, 4, v100
	v_and_b32_e32 v100, 0x70, v100
	v_lshl_add_u32 v132, v227, 1, s79
	v_add_u32_e32 v134, s79, v100
	v_lshl_add_u64 v[130:131], s[50:51], 0, v[100:101]
	ds_read_b64_tr_b16 v[244:245], v160 offset:32768
	ds_read_b64_tr_b16 v[246:247], v161 offset:34816
	s_waitcnt lgkmcnt(2)
	v_mfma_f32_32x32x16_bf16 v[48:63], v[72:75], v[156:159], v[48:63]
	v_lshlrev_b32_e32 v100, 9, v226
	v_add_u32_e32 v100, v132, v100
	ds_read_b64_tr_b16 v[156:157], v153 offset:32768
	ds_read_b64_tr_b16 v[158:159], v152 offset:32768
	s_waitcnt lgkmcnt(2)
	v_mfma_f32_32x32x16_bf16 v[48:63], v[68:71], v[244:247], v[48:63]
	s_waitcnt lgkmcnt(0)
	v_mfma_f32_32x32x16_bf16 v[48:63], v[64:67], v[156:159], v[48:63]
	v_lshl_add_u32 v64, v180, 2, s78
	ds_read_b128 v[76:79], v64
	ds_read_b128 v[72:75], v64 offset:32
	ds_read_b128 v[68:71], v64 offset:64
	ds_read_b128 v[64:67], v64 offset:96
	s_waitcnt lgkmcnt(3)
	v_mul_f32_e32 v0, v0, v76
	v_cvt_pk_bf16_f32 v0, v0, s0
	ds_write_b16 v100, v0
	v_mul_f32_e32 v0, v16, v76
	v_cvt_pk_bf16_f32 v0, v0, s0
	ds_write_b16 v100, v0 offset:64
	v_mul_f32_e32 v0, v1, v77
	v_cvt_pk_bf16_f32 v0, v0, s0
	ds_write_b16 v100, v0 offset:128
	v_mul_f32_e32 v0, v17, v77
	v_cvt_pk_bf16_f32 v0, v0, s0
	ds_write_b16 v100, v0 offset:192
	v_mul_f32_e32 v0, v2, v78
	v_cvt_pk_bf16_f32 v0, v0, s0
	ds_write_b16 v100, v0 offset:256
	v_mul_f32_e32 v0, v18, v78
	v_cvt_pk_bf16_f32 v0, v0, s0
	ds_write_b16 v100, v0 offset:320
	v_mul_f32_e32 v0, v3, v79
	v_cvt_pk_bf16_f32 v0, v0, s0
	ds_write_b16 v100, v0 offset:384
	v_mul_f32_e32 v0, v19, v79
	v_cvt_pk_bf16_f32 v0, v0, s0
	ds_write_b16 v100, v0 offset:448
	s_waitcnt lgkmcnt(10)
	v_mul_f32_e32 v0, v4, v72
	v_cvt_pk_bf16_f32 v0, v0, s0
	ds_write_b16 v100, v0 offset:1024
	v_mul_f32_e32 v0, v20, v72
	v_cvt_pk_bf16_f32 v0, v0, s0
	ds_write_b16 v100, v0 offset:1088
	v_mul_f32_e32 v0, v5, v73
	v_cvt_pk_bf16_f32 v0, v0, s0
	ds_write_b16 v100, v0 offset:1152
	v_mul_f32_e32 v0, v21, v73
	v_cvt_pk_bf16_f32 v0, v0, s0
	ds_write_b16 v100, v0 offset:1216
	v_mul_f32_e32 v0, v6, v74
	v_cvt_pk_bf16_f32 v0, v0, s0
	ds_write_b16 v100, v0 offset:1280
	v_mul_f32_e32 v0, v22, v74
	v_cvt_pk_bf16_f32 v0, v0, s0
	ds_write_b16 v100, v0 offset:1344
	v_mul_f32_e32 v0, v7, v75
	v_cvt_pk_bf16_f32 v0, v0, s0
	ds_write_b16 v100, v0 offset:1408
	v_mul_f32_e32 v0, v23, v75
	v_cvt_pk_bf16_f32 v0, v0, s0
	ds_write_b16 v100, v0 offset:1472
	v_lshlrev_b32_e32 v0, 7, v151
	v_add_u32_e32 v5, v132, v0
	s_waitcnt lgkmcnt(14)
	v_mul_f32_e32 v0, v8, v68
	v_cvt_pk_bf16_f32 v0, v0, s0
	ds_write_b16 v5, v0
	v_mul_f32_e32 v0, v24, v68
	v_cvt_pk_bf16_f32 v0, v0, s0
	ds_write_b16 v5, v0 offset:64
	v_mul_f32_e32 v0, v9, v69
	v_cvt_pk_bf16_f32 v0, v0, s0
	ds_write_b16 v100, v0 offset:2176
	v_mul_f32_e32 v0, v25, v69
	v_cvt_pk_bf16_f32 v0, v0, s0
	ds_write_b16 v100, v0 offset:2240
	v_mul_f32_e32 v0, v10, v70
	v_cvt_pk_bf16_f32 v0, v0, s0
	ds_write_b16 v100, v0 offset:2304
	v_mul_f32_e32 v0, v26, v70
	v_cvt_pk_bf16_f32 v0, v0, s0
	ds_write_b16 v100, v0 offset:2368
	v_mul_f32_e32 v0, v11, v71
	v_cvt_pk_bf16_f32 v0, v0, s0
	ds_write_b16 v100, v0 offset:2432
	v_mul_f32_e32 v0, v27, v71
	v_cvt_pk_bf16_f32 v0, v0, s0
	ds_write_b16 v100, v0 offset:2496
	v_mul_f32_e32 v0, v12, v64
	v_cvt_pk_bf16_f32 v0, v0, s0
	ds_write_b16 v100, v0 offset:3072
	v_mul_f32_e32 v0, v28, v64
	v_cvt_pk_bf16_f32 v0, v0, s0
	ds_write_b16 v100, v0 offset:3136
	v_mul_f32_e32 v0, v13, v65
	v_cvt_pk_bf16_f32 v0, v0, s0
	ds_write_b16 v100, v0 offset:3200
	v_mul_f32_e32 v0, v29, v65
	v_cvt_pk_bf16_f32 v0, v0, s0
	ds_write_b16 v100, v0 offset:3264
	v_mul_f32_e32 v0, v14, v66
	v_cvt_pk_bf16_f32 v0, v0, s0
	ds_write_b16 v100, v0 offset:3328
	v_mul_f32_e32 v0, v30, v66
	v_cvt_pk_bf16_f32 v0, v0, s0
	ds_write_b16 v100, v0 offset:3392
	v_mul_f32_e32 v0, v15, v67
	v_cvt_pk_bf16_f32 v0, v0, s0
	ds_write_b16 v100, v0 offset:3456
	v_mul_f32_e32 v0, v31, v67
	v_cvt_pk_bf16_f32 v0, v0, s0
	ds_write_b16 v100, v0 offset:3520
	v_add_u32_e32 v0, s85, v133
	v_add_u32_e32 v1, 8, v133
	v_add_u32_e32 v2, 16, v133
	v_add_u32_e32 v9, 24, v133
	v_lshl_add_u32 v7, v133, 7, v134
	v_mul_lo_u32 v8, v0, s84
	v_add_u32_e32 v6, s85, v1
	v_lshl_add_u32 v4, v1, 7, v134
	v_add_u32_e32 v3, s85, v2
	v_lshl_add_u32 v2, v2, 7, v134
	v_add_u32_e32 v1, s85, v9
	v_lshl_add_u32 v0, v9, 7, v134
	s_cbranch_vccnz .LBB0_130
	ds_read_b128 v[10:13], v7
	ds_read_b128 v[244:247], v4
	ds_read_b128 v[232:235], v2
	ds_read_b128 v[236:239], v0
	v_add_u32_e32 v14, s67, v8
	v_ashrrev_i32_e32 v15, 31, v14
	v_lshlrev_b64 v[14:15], 13, v[14:15]
	v_lshl_add_u64 v[14:15], v[130:131], 0, v[14:15]
	s_waitcnt lgkmcnt(3)
	global_store_dwordx4 v[14:15], v[10:13], off
	v_mul_lo_u32 v9, v6, s84
	v_add_u32_e32 v14, s67, v9
	v_ashrrev_i32_e32 v15, 31, v14
	v_lshlrev_b64 v[14:15], 13, v[14:15]
	v_lshl_add_u64 v[14:15], v[130:131], 0, v[14:15]
	s_waitcnt lgkmcnt(2)
	global_store_dwordx4 v[14:15], v[244:247], off
	v_mul_lo_u32 v9, v3, s84
	v_add_u32_e32 v14, s67, v9
	v_ashrrev_i32_e32 v15, 31, v14
	v_lshlrev_b64 v[14:15], 13, v[14:15]
	v_lshl_add_u64 v[14:15], v[130:131], 0, v[14:15]
	s_waitcnt lgkmcnt(1)
	global_store_dwordx4 v[14:15], v[232:235], off
	v_mul_lo_u32 v9, v1, s84
	v_add_u32_e32 v14, s67, v9
	v_ashrrev_i32_e32 v15, 31, v14
	v_lshlrev_b64 v[14:15], 13, v[14:15]
	v_lshl_add_u64 v[14:15], v[130:131], 0, v[14:15]
	s_waitcnt lgkmcnt(0)
	global_store_dwordx4 v[14:15], v[236:239], off
